# branch epilogue: gate and merged loads issued interleaved per step (G0,M0,G1,M1..) so the first steps start before all 16 gate loads have landed; otherwise same as v25
# speedup vs baseline: 1.0132x; 1.0132x over previous
; __device__ __forceinline__ unsigned pk2(float lo, float hi) { f32x2_t v = {lo, hi}; bf16x2_t b = __builtin_convertvector(v, bf16x2_t); return __builtin_bit_cast(unsigned, b); }
; __device__ __forceinline__ float bflo(unsigned w) { return __uint_as_float(w << 16); }
; __device__ __forceinline__ float bfhi(unsigned w) { return __uint_as_float(w & 0xffff0000u); }
;     __device__ __forceinline__ void operator()(const f32x4 (&acc)[2][2][4][2], const Unit& us, int wr, int wc, int fr, int fq) const {
;         const int br = us.pm >> 6; Unit u; u.pm = us.pm & 63; u.pn = us.pn & 3;
;         const int row0 = u.pm * 256 + wr * 64 + fr;
; #pragma unroll
;         for (int ai = 0; ai < 2; ++ai)
; #pragma unroll
;             for (int m = 0; m < 4; ++m) {
;                 const int row = row0 + ai * 128 + m * 16;
; #pragma unroll
;                 for (int bj = 0; bj < 2; ++bj) {
;                     const int col = u.pn * 256 + bj * 128 + wc * 32 + 8 * fq;
;                     const u32x4 g = *(const u32x4*)(gates + (unsigned)(row * NG + br * DM + col));
;                     const f32x4 v0 = acc[ai][bj][m][0], v1 = acc[ai][bj][m][1];
;                     float o[8];
;                     o[0] = bflo(g.x) * v0[0]; o[1] = bfhi(g.x) * v0[1]; o[2] = bflo(g.y) * v0[2]; o[3] = bfhi(g.y) * v0[3];
;                     o[4] = bflo(g.z) * v1[0]; o[5] = bfhi(g.z) * v1[1]; o[6] = bflo(g.w) * v1[2]; o[7] = bfhi(g.w) * v1[3];
;                     bf16_t* dst = merged + (unsigned)(row * DM + col);
;                     if (br > 0) {
;                         const u32x4 p = *(const u32x4*)dst;
;                         o[0] += bflo(p.x); o[1] += bfhi(p.x); o[2] += bflo(p.y); o[3] += bfhi(p.y);
;                         o[4] += bflo(p.z); o[5] += bfhi(p.z); o[6] += bflo(p.w); o[7] += bfhi(p.w);
;                     }
;                     u32x4 w; w.x = pk2(o[0], o[1]); w.y = pk2(o[2], o[3]); w.z = pk2(o[4], o[5]); w.w = pk2(o[6], o[7]);
;                     *(u32x4*)dst = w;
;                 }
;                 asm volatile("" ::: "memory");
;             }
.LBB0_350:
	s_lshl_b32 s3, s44, 8
	s_and_b32 s3, s3, 0x3f00
	v_add_u32_e32 v145, s3, v213
	s_lshl_b32 s3, s42, 8
	s_ashr_i32 s2, s44, 6
	s_and_b32 s3, s3, 0x300
	v_or_b32_e32 v144, s3, v143
	v_mul_lo_u32 v64, v145, s76
	v_lshlrev_b32_e32 v237, 10, v145
	v_lshl_add_u32 v64, s2, 10, v64
	v_add_lshl_u32 v237, v237, v144, 1
	v_add_lshl_u32 v64, v64, v144, 1
	v_mov_b64_e32 v[234:235], v[204:205]
	v_mov_b32_e32 v236, v212
	v_mov_b32_e32 v250, v237
	v_mov_b64_e32 v[204:205], 0xff
	v_mov_b32_e32 v212, 1
	v_mov_b32_e32 v242, 0x358637bd
	s_cmp_lt_i32 s2, 1
	s_cbranch_scc1 .Lbr_ep_first
	global_load_dwordx4 v[154:157], v64, s[36:37]
	global_load_dwordx4 v[226:229], v250, s[6:7]
	global_load_dwordx4 v[158:161], v64, s[36:37] offset:256
	v_add_u32_e32 v64, 0x18000, v64
	global_load_dwordx4 v[230:233], v250, s[6:7] offset:256
	v_add_u32_e32 v250, 0x8000, v250
	global_load_dwordx4 v[162:165], v64, s[36:37]
	global_load_dwordx4 v[238:241], v250, s[6:7]
	global_load_dwordx4 v[166:169], v64, s[36:37] offset:256
	v_add_u32_e32 v64, 0x18000, v64
	global_load_dwordx4 v[246:249], v250, s[6:7] offset:256
	v_add_u32_e32 v250, 0x8000, v250
	global_load_dwordx4 v[170:173], v64, s[36:37]
	global_load_dwordx4 v[144:147], v250, s[6:7]
	global_load_dwordx4 v[174:177], v64, s[36:37] offset:256
	v_add_u32_e32 v64, 0x18000, v64
	global_load_dwordx4 v[148:151], v250, s[6:7] offset:256
	v_add_u32_e32 v250, 0x8000, v250
	global_load_dwordx4 v[178:181], v64, s[36:37]
	global_load_dwordx4 v[182:185], v64, s[36:37] offset:256
	v_add_u32_e32 v64, 0x78000, v64
	global_load_dwordx4 v[186:189], v64, s[36:37]
	global_load_dwordx4 v[190:193], v64, s[36:37] offset:256
	v_add_u32_e32 v64, 0x18000, v64
	global_load_dwordx4 v[194:197], v64, s[36:37]
	global_load_dwordx4 v[198:201], v64, s[36:37] offset:256
	v_add_u32_e32 v64, 0x18000, v64
	global_load_dwordx4 v[206:209], v64, s[36:37]
	global_load_dwordx4 v[214:217], v64, s[36:37] offset:256
	v_add_u32_e32 v64, 0x18000, v64
	global_load_dwordx4 v[218:221], v64, s[36:37]
	global_load_dwordx4 v[222:225], v64, s[36:37] offset:256
	s_waitcnt vmcnt(20)
	v_lshlrev_b32_e32 v138, 16, v154
	v_and_b32_e32 v139, 0xffff0000, v154
	v_lshlrev_b32_e32 v152, 16, v155
	v_and_b32_e32 v153, 0xffff0000, v155
	v_lshlrev_b32_e32 v210, 16, v156
	v_and_b32_e32 v211, 0xffff0000, v156
	v_lshlrev_b32_e32 v202, 16, v157
	v_and_b32_e32 v203, 0xffff0000, v157
	v_pk_mul_f32 v[126:127], v[126:127], v[138:139]
	v_pk_mul_f32 v[128:129], v[128:129], v[152:153]
	v_pk_mul_f32 v[122:123], v[122:123], v[210:211]
	v_pk_mul_f32 v[124:125], v[124:125], v[202:203]
	v_lshlrev_b32_e32 v138, 16, v226
	v_and_b32_e32 v139, 0xffff0000, v226
	v_lshlrev_b32_e32 v152, 16, v227
	v_and_b32_e32 v153, 0xffff0000, v227
	v_lshlrev_b32_e32 v210, 16, v228
	v_and_b32_e32 v211, 0xffff0000, v228
	v_lshlrev_b32_e32 v202, 16, v229
	v_and_b32_e32 v203, 0xffff0000, v229
	v_pk_add_f32 v[126:127], v[126:127], v[138:139]
	v_pk_add_f32 v[128:129], v[128:129], v[152:153]
	v_pk_add_f32 v[122:123], v[122:123], v[210:211]
	v_pk_add_f32 v[124:125], v[124:125], v[202:203]
	v_cvt_pk_bf16_f32 v126, v126, v127
	v_cvt_pk_bf16_f32 v127, v128, v129
	v_cvt_pk_bf16_f32 v128, v122, v123
	v_cvt_pk_bf16_f32 v129, v124, v125
	global_store_dwordx4 v237, v[126:129], s[6:7]
	global_load_dwordx4 v[226:229], v250, s[6:7]
	s_waitcnt vmcnt(20)
	v_lshlrev_b32_e32 v138, 16, v158
	v_and_b32_e32 v139, 0xffff0000, v158
	v_lshlrev_b32_e32 v152, 16, v159
	v_and_b32_e32 v153, 0xffff0000, v159
	v_lshlrev_b32_e32 v210, 16, v160
	v_and_b32_e32 v211, 0xffff0000, v160
	v_lshlrev_b32_e32 v202, 16, v161
	v_and_b32_e32 v203, 0xffff0000, v161
	v_pk_mul_f32 v[114:115], v[114:115], v[138:139]
	v_pk_mul_f32 v[116:117], v[116:117], v[152:153]
	v_pk_mul_f32 v[118:119], v[118:119], v[210:211]
	v_pk_mul_f32 v[120:121], v[120:121], v[202:203]
	v_lshlrev_b32_e32 v138, 16, v230
	v_and_b32_e32 v139, 0xffff0000, v230
	v_lshlrev_b32_e32 v152, 16, v231
	v_and_b32_e32 v153, 0xffff0000, v231
	v_lshlrev_b32_e32 v210, 16, v232
	v_and_b32_e32 v211, 0xffff0000, v232
	v_lshlrev_b32_e32 v202, 16, v233
	v_and_b32_e32 v203, 0xffff0000, v233
	v_pk_add_f32 v[114:115], v[114:115], v[138:139]
	v_pk_add_f32 v[116:117], v[116:117], v[152:153]
	v_pk_add_f32 v[118:119], v[118:119], v[210:211]
	v_pk_add_f32 v[120:121], v[120:121], v[202:203]
	v_cvt_pk_bf16_f32 v114, v114, v115
	v_cvt_pk_bf16_f32 v115, v116, v117
	v_cvt_pk_bf16_f32 v116, v118, v119
	v_cvt_pk_bf16_f32 v117, v120, v121
	global_store_dwordx4 v237, v[114:117], s[6:7] offset:256
	v_add_u32_e32 v237, 0x8000, v237
	global_load_dwordx4 v[230:233], v250, s[6:7] offset:256
	v_add_u32_e32 v250, 0x28000, v250
	s_waitcnt vmcnt(20)
	v_lshlrev_b32_e32 v138, 16, v162
	v_and_b32_e32 v139, 0xffff0000, v162
	v_lshlrev_b32_e32 v152, 16, v163
	v_and_b32_e32 v153, 0xffff0000, v163
	v_lshlrev_b32_e32 v210, 16, v164
	v_and_b32_e32 v211, 0xffff0000, v164
	v_lshlrev_b32_e32 v202, 16, v165
	v_and_b32_e32 v203, 0xffff0000, v165
	v_pk_mul_f32 v[110:111], v[110:111], v[138:139]
	v_pk_mul_f32 v[112:113], v[112:113], v[152:153]
	v_pk_mul_f32 v[106:107], v[106:107], v[210:211]
	v_pk_mul_f32 v[108:109], v[108:109], v[202:203]
	v_lshlrev_b32_e32 v138, 16, v238
	v_and_b32_e32 v139, 0xffff0000, v238
	v_lshlrev_b32_e32 v152, 16, v239
	v_and_b32_e32 v153, 0xffff0000, v239
	v_lshlrev_b32_e32 v210, 16, v240
	v_and_b32_e32 v211, 0xffff0000, v240
	v_lshlrev_b32_e32 v202, 16, v241
	v_and_b32_e32 v203, 0xffff0000, v241
	v_pk_add_f32 v[110:111], v[110:111], v[138:139]
	v_pk_add_f32 v[112:113], v[112:113], v[152:153]
	v_pk_add_f32 v[106:107], v[106:107], v[210:211]
	v_pk_add_f32 v[108:109], v[108:109], v[202:203]
	v_cvt_pk_bf16_f32 v110, v110, v111
	v_cvt_pk_bf16_f32 v111, v112, v113
	v_cvt_pk_bf16_f32 v112, v106, v107
	v_cvt_pk_bf16_f32 v113, v108, v109
	global_store_dwordx4 v237, v[110:113], s[6:7]
	global_load_dwordx4 v[238:241], v250, s[6:7]
	s_waitcnt vmcnt(20)
; __device__ __forceinline__ unsigned pk2(float lo, float hi) { f32x2_t v = {lo, hi}; bf16x2_t b = __builtin_convertvector(v, bf16x2_t); return __builtin_bit_cast(unsigned, b); }
; __device__ __forceinline__ float bflo(unsigned w) { return __uint_as_float(w << 16); }
; __device__ __forceinline__ float bfhi(unsigned w) { return __uint_as_float(w & 0xffff0000u); }
;     __device__ __forceinline__ void operator()(const f32x4 (&acc)[2][2][4][2], const Unit& us, int wr, int wc, int fr, int fq) const {
;     ...
;                 for (int bj = 0; bj < 2; ++bj) {
;                     const int col = u.pn * 256 + bj * 128 + wc * 32 + 8 * fq;
;                     const u32x4 g = *(const u32x4*)(gates + (unsigned)(row * NG + br * DM + col));
;                     const f32x4 v0 = acc[ai][bj][m][0], v1 = acc[ai][bj][m][1];
;                     float o[8];
;                     o[0] = bflo(g.x) * v0[0]; o[1] = bfhi(g.x) * v0[1]; o[2] = bflo(g.y) * v0[2]; o[3] = bfhi(g.y) * v0[3];
;                     o[4] = bflo(g.z) * v1[0]; o[5] = bfhi(g.z) * v1[1]; o[6] = bflo(g.w) * v1[2]; o[7] = bfhi(g.w) * v1[3];
;                     bf16_t* dst = merged + (unsigned)(row * DM + col);
;                     if (br > 0) {
;                         const u32x4 p = *(const u32x4*)dst;
;                         o[0] += bflo(p.x); o[1] += bfhi(p.x); o[2] += bflo(p.y); o[3] += bfhi(p.y);
;                         o[4] += bflo(p.z); o[5] += bfhi(p.z); o[6] += bflo(p.w); o[7] += bfhi(p.w);
;                     }
;                     u32x4 w; w.x = pk2(o[0], o[1]); w.y = pk2(o[2], o[3]); w.z = pk2(o[4], o[5]); w.w = pk2(o[6], o[7]);
;                     *(u32x4*)dst = w;
;                 }
	v_lshlrev_b32_e32 v138, 16, v166
	v_and_b32_e32 v139, 0xffff0000, v166
	v_lshlrev_b32_e32 v152, 16, v167
	v_and_b32_e32 v153, 0xffff0000, v167
	v_lshlrev_b32_e32 v210, 16, v168
	v_and_b32_e32 v211, 0xffff0000, v168
	v_lshlrev_b32_e32 v202, 16, v169
	v_and_b32_e32 v203, 0xffff0000, v169
	v_pk_mul_f32 v[98:99], v[98:99], v[138:139]
	v_pk_mul_f32 v[100:101], v[100:101], v[152:153]
	v_pk_mul_f32 v[102:103], v[102:103], v[210:211]
	v_pk_mul_f32 v[104:105], v[104:105], v[202:203]
	v_lshlrev_b32_e32 v138, 16, v246
	v_and_b32_e32 v139, 0xffff0000, v246
	v_lshlrev_b32_e32 v152, 16, v247
	v_and_b32_e32 v153, 0xffff0000, v247
	v_lshlrev_b32_e32 v210, 16, v248
	v_and_b32_e32 v211, 0xffff0000, v248
	v_lshlrev_b32_e32 v202, 16, v249
	v_and_b32_e32 v203, 0xffff0000, v249
	v_pk_add_f32 v[98:99], v[98:99], v[138:139]
	v_pk_add_f32 v[100:101], v[100:101], v[152:153]
	v_pk_add_f32 v[102:103], v[102:103], v[210:211]
	v_pk_add_f32 v[104:105], v[104:105], v[202:203]
	v_cvt_pk_bf16_f32 v98, v98, v99
	v_cvt_pk_bf16_f32 v99, v100, v101
	v_cvt_pk_bf16_f32 v100, v102, v103
	v_cvt_pk_bf16_f32 v101, v104, v105
	global_store_dwordx4 v237, v[98:101], s[6:7] offset:256
	v_add_u32_e32 v237, 0x8000, v237
	global_load_dwordx4 v[246:249], v250, s[6:7] offset:256
	v_add_u32_e32 v250, 0x8000, v250
	s_waitcnt vmcnt(20)
	v_lshlrev_b32_e32 v138, 16, v170
	v_and_b32_e32 v139, 0xffff0000, v170
	v_lshlrev_b32_e32 v152, 16, v171
	v_and_b32_e32 v153, 0xffff0000, v171
	v_lshlrev_b32_e32 v210, 16, v172
	v_and_b32_e32 v211, 0xffff0000, v172
	v_lshlrev_b32_e32 v202, 16, v173
	v_and_b32_e32 v203, 0xffff0000, v173
	v_pk_mul_f32 v[94:95], v[94:95], v[138:139]
	v_pk_mul_f32 v[96:97], v[96:97], v[152:153]
	v_pk_mul_f32 v[90:91], v[90:91], v[210:211]
	v_pk_mul_f32 v[92:93], v[92:93], v[202:203]
	v_lshlrev_b32_e32 v138, 16, v144
	v_and_b32_e32 v139, 0xffff0000, v144
	v_lshlrev_b32_e32 v152, 16, v145
	v_and_b32_e32 v153, 0xffff0000, v145
	v_lshlrev_b32_e32 v210, 16, v146
	v_and_b32_e32 v211, 0xffff0000, v146
	v_lshlrev_b32_e32 v202, 16, v147
	v_and_b32_e32 v203, 0xffff0000, v147
	v_pk_add_f32 v[94:95], v[94:95], v[138:139]
	v_pk_add_f32 v[96:97], v[96:97], v[152:153]
	v_pk_add_f32 v[90:91], v[90:91], v[210:211]
	v_pk_add_f32 v[92:93], v[92:93], v[202:203]
	v_cvt_pk_bf16_f32 v94, v94, v95
	v_cvt_pk_bf16_f32 v95, v96, v97
	v_cvt_pk_bf16_f32 v96, v90, v91
	v_cvt_pk_bf16_f32 v97, v92, v93
	global_store_dwordx4 v237, v[94:97], s[6:7]
	global_load_dwordx4 v[144:147], v250, s[6:7]
	s_waitcnt vmcnt(20)
	v_lshlrev_b32_e32 v138, 16, v174
	v_and_b32_e32 v139, 0xffff0000, v174
	v_lshlrev_b32_e32 v152, 16, v175
	v_and_b32_e32 v153, 0xffff0000, v175
	v_lshlrev_b32_e32 v210, 16, v176
	v_and_b32_e32 v211, 0xffff0000, v176
	v_lshlrev_b32_e32 v202, 16, v177
	v_and_b32_e32 v203, 0xffff0000, v177
	v_pk_mul_f32 v[82:83], v[82:83], v[138:139]
	v_pk_mul_f32 v[84:85], v[84:85], v[152:153]
	v_pk_mul_f32 v[86:87], v[86:87], v[210:211]
	v_pk_mul_f32 v[88:89], v[88:89], v[202:203]
	v_lshlrev_b32_e32 v138, 16, v148
	v_and_b32_e32 v139, 0xffff0000, v148
	v_lshlrev_b32_e32 v152, 16, v149
	v_and_b32_e32 v153, 0xffff0000, v149
	v_lshlrev_b32_e32 v210, 16, v150
	v_and_b32_e32 v211, 0xffff0000, v150
	v_lshlrev_b32_e32 v202, 16, v151
	v_and_b32_e32 v203, 0xffff0000, v151
	v_pk_add_f32 v[82:83], v[82:83], v[138:139]
	v_pk_add_f32 v[84:85], v[84:85], v[152:153]
	v_pk_add_f32 v[86:87], v[86:87], v[210:211]
	v_pk_add_f32 v[88:89], v[88:89], v[202:203]
	v_cvt_pk_bf16_f32 v82, v82, v83
	v_cvt_pk_bf16_f32 v83, v84, v85
	v_cvt_pk_bf16_f32 v84, v86, v87
	v_cvt_pk_bf16_f32 v85, v88, v89
	global_store_dwordx4 v237, v[82:85], s[6:7] offset:256
	v_add_u32_e32 v237, 0x8000, v237
	global_load_dwordx4 v[148:151], v250, s[6:7] offset:256
	v_add_u32_e32 v250, 0x8000, v250
	s_waitcnt vmcnt(10)
	v_lshlrev_b32_e32 v138, 16, v178
	v_and_b32_e32 v139, 0xffff0000, v178
	v_lshlrev_b32_e32 v152, 16, v179
	v_and_b32_e32 v153, 0xffff0000, v179
	v_lshlrev_b32_e32 v210, 16, v180
	v_and_b32_e32 v211, 0xffff0000, v180
	v_lshlrev_b32_e32 v202, 16, v181
	v_and_b32_e32 v203, 0xffff0000, v181
	v_pk_mul_f32 v[78:79], v[78:79], v[138:139]
	v_pk_mul_f32 v[80:81], v[80:81], v[152:153]
	v_pk_mul_f32 v[74:75], v[74:75], v[210:211]
	v_pk_mul_f32 v[76:77], v[76:77], v[202:203]
	v_lshlrev_b32_e32 v138, 16, v226
	v_and_b32_e32 v139, 0xffff0000, v226
	v_lshlrev_b32_e32 v152, 16, v227
	v_and_b32_e32 v153, 0xffff0000, v227
	v_lshlrev_b32_e32 v210, 16, v228
	v_and_b32_e32 v211, 0xffff0000, v228
	v_lshlrev_b32_e32 v202, 16, v229
	v_and_b32_e32 v203, 0xffff0000, v229
	v_pk_add_f32 v[78:79], v[78:79], v[138:139]
	v_pk_add_f32 v[80:81], v[80:81], v[152:153]
	v_pk_add_f32 v[74:75], v[74:75], v[210:211]
	v_pk_add_f32 v[76:77], v[76:77], v[202:203]
	v_cvt_pk_bf16_f32 v78, v78, v79
	v_cvt_pk_bf16_f32 v79, v80, v81
	v_cvt_pk_bf16_f32 v80, v74, v75
	v_cvt_pk_bf16_f32 v81, v76, v77
	global_store_dwordx4 v237, v[78:81], s[6:7]
	global_load_dwordx4 v[226:229], v250, s[6:7]
	s_waitcnt vmcnt(10)
	v_lshlrev_b32_e32 v138, 16, v182
	v_and_b32_e32 v139, 0xffff0000, v182
	v_lshlrev_b32_e32 v152, 16, v183
	v_and_b32_e32 v153, 0xffff0000, v183
	v_lshlrev_b32_e32 v210, 16, v184
	v_and_b32_e32 v211, 0xffff0000, v184
	v_lshlrev_b32_e32 v202, 16, v185
	v_and_b32_e32 v203, 0xffff0000, v185
	v_pk_mul_f32 v[66:67], v[66:67], v[138:139]
	v_pk_mul_f32 v[68:69], v[68:69], v[152:153]
	v_pk_mul_f32 v[70:71], v[70:71], v[210:211]
	v_pk_mul_f32 v[72:73], v[72:73], v[202:203]
	v_lshlrev_b32_e32 v138, 16, v230
	v_and_b32_e32 v139, 0xffff0000, v230
	v_lshlrev_b32_e32 v152, 16, v231
	v_and_b32_e32 v153, 0xffff0000, v231
	v_lshlrev_b32_e32 v210, 16, v232
	v_and_b32_e32 v211, 0xffff0000, v232
	v_lshlrev_b32_e32 v202, 16, v233
	v_and_b32_e32 v203, 0xffff0000, v233
	v_pk_add_f32 v[66:67], v[66:67], v[138:139]
	v_pk_add_f32 v[68:69], v[68:69], v[152:153]
	v_pk_add_f32 v[70:71], v[70:71], v[210:211]
	v_pk_add_f32 v[72:73], v[72:73], v[202:203]
	v_cvt_pk_bf16_f32 v66, v66, v67
	v_cvt_pk_bf16_f32 v67, v68, v69
	v_cvt_pk_bf16_f32 v68, v70, v71
	v_cvt_pk_bf16_f32 v69, v72, v73
	global_store_dwordx4 v237, v[66:69], s[6:7] offset:256
	v_add_u32_e32 v237, 0x28000, v237
	global_load_dwordx4 v[230:233], v250, s[6:7] offset:256
	v_add_u32_e32 v250, 0x8000, v250
	s_waitcnt vmcnt(10)
; __device__ __forceinline__ unsigned pk2(float lo, float hi) { f32x2_t v = {lo, hi}; bf16x2_t b = __builtin_convertvector(v, bf16x2_t); return __builtin_bit_cast(unsigned, b); }
; __device__ __forceinline__ float bflo(unsigned w) { return __uint_as_float(w << 16); }
; __device__ __forceinline__ float bfhi(unsigned w) { return __uint_as_float(w & 0xffff0000u); }
;     __device__ __forceinline__ void operator()(const f32x4 (&acc)[2][2][4][2], const Unit& us, int wr, int wc, int fr, int fq) const {
;     ...
;                 for (int bj = 0; bj < 2; ++bj) {
;                     const int col = u.pn * 256 + bj * 128 + wc * 32 + 8 * fq;
;                     const u32x4 g = *(const u32x4*)(gates + (unsigned)(row * NG + br * DM + col));
;                     const f32x4 v0 = acc[ai][bj][m][0], v1 = acc[ai][bj][m][1];
;                     float o[8];
;                     o[0] = bflo(g.x) * v0[0]; o[1] = bfhi(g.x) * v0[1]; o[2] = bflo(g.y) * v0[2]; o[3] = bfhi(g.y) * v0[3];
;                     o[4] = bflo(g.z) * v1[0]; o[5] = bfhi(g.z) * v1[1]; o[6] = bflo(g.w) * v1[2]; o[7] = bfhi(g.w) * v1[3];
;                     bf16_t* dst = merged + (unsigned)(row * DM + col);
;                     if (br > 0) {
;                         const u32x4 p = *(const u32x4*)dst;
;                         o[0] += bflo(p.x); o[1] += bfhi(p.x); o[2] += bflo(p.y); o[3] += bfhi(p.y);
;                         o[4] += bflo(p.z); o[5] += bfhi(p.z); o[6] += bflo(p.w); o[7] += bfhi(p.w);
;                     }
;                     u32x4 w; w.x = pk2(o[0], o[1]); w.y = pk2(o[2], o[3]); w.z = pk2(o[4], o[5]); w.w = pk2(o[6], o[7]);
;                     *(u32x4*)dst = w;
;                 }
	v_lshlrev_b32_e32 v138, 16, v186
	v_and_b32_e32 v139, 0xffff0000, v186
	v_lshlrev_b32_e32 v152, 16, v187
	v_and_b32_e32 v153, 0xffff0000, v187
	v_lshlrev_b32_e32 v210, 16, v188
	v_and_b32_e32 v211, 0xffff0000, v188
	v_lshlrev_b32_e32 v202, 16, v189
	v_and_b32_e32 v203, 0xffff0000, v189
	v_pk_mul_f32 v[60:61], v[60:61], v[138:139]
	v_pk_mul_f32 v[62:63], v[62:63], v[152:153]
	v_pk_mul_f32 v[56:57], v[56:57], v[210:211]
	v_pk_mul_f32 v[58:59], v[58:59], v[202:203]
	v_lshlrev_b32_e32 v138, 16, v238
	v_and_b32_e32 v139, 0xffff0000, v238
	v_lshlrev_b32_e32 v152, 16, v239
	v_and_b32_e32 v153, 0xffff0000, v239
	v_lshlrev_b32_e32 v210, 16, v240
	v_and_b32_e32 v211, 0xffff0000, v240
	v_lshlrev_b32_e32 v202, 16, v241
	v_and_b32_e32 v203, 0xffff0000, v241
	v_pk_add_f32 v[60:61], v[60:61], v[138:139]
	v_pk_add_f32 v[62:63], v[62:63], v[152:153]
	v_pk_add_f32 v[56:57], v[56:57], v[210:211]
	v_pk_add_f32 v[58:59], v[58:59], v[202:203]
	v_cvt_pk_bf16_f32 v60, v60, v61
	v_cvt_pk_bf16_f32 v61, v62, v63
	v_cvt_pk_bf16_f32 v62, v56, v57
	v_cvt_pk_bf16_f32 v63, v58, v59
	global_store_dwordx4 v237, v[60:63], s[6:7]
	global_load_dwordx4 v[238:241], v250, s[6:7]
	s_waitcnt vmcnt(10)
	v_lshlrev_b32_e32 v138, 16, v190
	v_and_b32_e32 v139, 0xffff0000, v190
	v_lshlrev_b32_e32 v152, 16, v191
	v_and_b32_e32 v153, 0xffff0000, v191
	v_lshlrev_b32_e32 v210, 16, v192
	v_and_b32_e32 v211, 0xffff0000, v192
	v_lshlrev_b32_e32 v202, 16, v193
	v_and_b32_e32 v203, 0xffff0000, v193
	v_pk_mul_f32 v[48:49], v[48:49], v[138:139]
	v_pk_mul_f32 v[50:51], v[50:51], v[152:153]
	v_pk_mul_f32 v[52:53], v[52:53], v[210:211]
	v_pk_mul_f32 v[54:55], v[54:55], v[202:203]
	v_lshlrev_b32_e32 v138, 16, v246
	v_and_b32_e32 v139, 0xffff0000, v246
	v_lshlrev_b32_e32 v152, 16, v247
	v_and_b32_e32 v153, 0xffff0000, v247
	v_lshlrev_b32_e32 v210, 16, v248
	v_and_b32_e32 v211, 0xffff0000, v248
	v_lshlrev_b32_e32 v202, 16, v249
	v_and_b32_e32 v203, 0xffff0000, v249
	v_pk_add_f32 v[48:49], v[48:49], v[138:139]
	v_pk_add_f32 v[50:51], v[50:51], v[152:153]
	v_pk_add_f32 v[52:53], v[52:53], v[210:211]
	v_pk_add_f32 v[54:55], v[54:55], v[202:203]
	v_cvt_pk_bf16_f32 v48, v48, v49
	v_cvt_pk_bf16_f32 v49, v50, v51
	v_cvt_pk_bf16_f32 v50, v52, v53
	v_cvt_pk_bf16_f32 v51, v54, v55
	global_store_dwordx4 v237, v[48:51], s[6:7] offset:256
	v_add_u32_e32 v237, 0x8000, v237
	global_load_dwordx4 v[246:249], v250, s[6:7] offset:256
	s_waitcnt vmcnt(10)
	v_lshlrev_b32_e32 v138, 16, v194
	v_and_b32_e32 v139, 0xffff0000, v194
	v_lshlrev_b32_e32 v152, 16, v195
	v_and_b32_e32 v153, 0xffff0000, v195
	v_lshlrev_b32_e32 v210, 16, v196
	v_and_b32_e32 v211, 0xffff0000, v196
	v_lshlrev_b32_e32 v202, 16, v197
	v_and_b32_e32 v203, 0xffff0000, v197
	v_pk_mul_f32 v[44:45], v[44:45], v[138:139]
	v_pk_mul_f32 v[46:47], v[46:47], v[152:153]
	v_pk_mul_f32 v[40:41], v[40:41], v[210:211]
	v_pk_mul_f32 v[42:43], v[42:43], v[202:203]
	v_lshlrev_b32_e32 v138, 16, v144
	v_and_b32_e32 v139, 0xffff0000, v144
	v_lshlrev_b32_e32 v152, 16, v145
	v_and_b32_e32 v153, 0xffff0000, v145
	v_lshlrev_b32_e32 v210, 16, v146
	v_and_b32_e32 v211, 0xffff0000, v146
	v_lshlrev_b32_e32 v202, 16, v147
	v_and_b32_e32 v203, 0xffff0000, v147
	v_pk_add_f32 v[44:45], v[44:45], v[138:139]
	v_pk_add_f32 v[46:47], v[46:47], v[152:153]
	v_pk_add_f32 v[40:41], v[40:41], v[210:211]
	v_pk_add_f32 v[42:43], v[42:43], v[202:203]
	v_cvt_pk_bf16_f32 v44, v44, v45
	v_cvt_pk_bf16_f32 v45, v46, v47
	v_cvt_pk_bf16_f32 v46, v40, v41
	v_cvt_pk_bf16_f32 v47, v42, v43
	global_store_dwordx4 v237, v[44:47], s[6:7]
	s_waitcnt vmcnt(9)
	v_lshlrev_b32_e32 v138, 16, v198
	v_and_b32_e32 v139, 0xffff0000, v198
	v_lshlrev_b32_e32 v152, 16, v199
	v_and_b32_e32 v153, 0xffff0000, v199
	v_lshlrev_b32_e32 v210, 16, v200
	v_and_b32_e32 v211, 0xffff0000, v200
	v_lshlrev_b32_e32 v202, 16, v201
	v_and_b32_e32 v203, 0xffff0000, v201
	v_pk_mul_f32 v[32:33], v[32:33], v[138:139]
	v_pk_mul_f32 v[34:35], v[34:35], v[152:153]
	v_pk_mul_f32 v[36:37], v[36:37], v[210:211]
	v_pk_mul_f32 v[38:39], v[38:39], v[202:203]
	v_lshlrev_b32_e32 v138, 16, v148
	v_and_b32_e32 v139, 0xffff0000, v148
	v_lshlrev_b32_e32 v152, 16, v149
	v_and_b32_e32 v153, 0xffff0000, v149
	v_lshlrev_b32_e32 v210, 16, v150
	v_and_b32_e32 v211, 0xffff0000, v150
	v_lshlrev_b32_e32 v202, 16, v151
	v_and_b32_e32 v203, 0xffff0000, v151
	v_pk_add_f32 v[32:33], v[32:33], v[138:139]
	v_pk_add_f32 v[34:35], v[34:35], v[152:153]
	v_pk_add_f32 v[36:37], v[36:37], v[210:211]
	v_pk_add_f32 v[38:39], v[38:39], v[202:203]
	v_cvt_pk_bf16_f32 v32, v32, v33
	v_cvt_pk_bf16_f32 v33, v34, v35
	v_cvt_pk_bf16_f32 v34, v36, v37
	v_cvt_pk_bf16_f32 v35, v38, v39
	global_store_dwordx4 v237, v[32:35], s[6:7] offset:256
	v_add_u32_e32 v237, 0x8000, v237
	s_waitcnt vmcnt(8)
	v_lshlrev_b32_e32 v138, 16, v206
	v_and_b32_e32 v139, 0xffff0000, v206
	v_lshlrev_b32_e32 v152, 16, v207
	v_and_b32_e32 v153, 0xffff0000, v207
	v_lshlrev_b32_e32 v210, 16, v208
	v_and_b32_e32 v211, 0xffff0000, v208
	v_lshlrev_b32_e32 v202, 16, v209
	v_and_b32_e32 v203, 0xffff0000, v209
	v_pk_mul_f32 v[28:29], v[28:29], v[138:139]
	v_pk_mul_f32 v[30:31], v[30:31], v[152:153]
	v_pk_mul_f32 v[24:25], v[24:25], v[210:211]
	v_pk_mul_f32 v[26:27], v[26:27], v[202:203]
	v_lshlrev_b32_e32 v138, 16, v226
	v_and_b32_e32 v139, 0xffff0000, v226
	v_lshlrev_b32_e32 v152, 16, v227
	v_and_b32_e32 v153, 0xffff0000, v227
	v_lshlrev_b32_e32 v210, 16, v228
	v_and_b32_e32 v211, 0xffff0000, v228
	v_lshlrev_b32_e32 v202, 16, v229
	v_and_b32_e32 v203, 0xffff0000, v229
	v_pk_add_f32 v[28:29], v[28:29], v[138:139]
	v_pk_add_f32 v[30:31], v[30:31], v[152:153]
	v_pk_add_f32 v[24:25], v[24:25], v[210:211]
	v_pk_add_f32 v[26:27], v[26:27], v[202:203]
	v_cvt_pk_bf16_f32 v28, v28, v29
	v_cvt_pk_bf16_f32 v29, v30, v31
	v_cvt_pk_bf16_f32 v30, v24, v25
	v_cvt_pk_bf16_f32 v31, v26, v27
	global_store_dwordx4 v237, v[28:31], s[6:7]
	s_waitcnt vmcnt(7)
; __device__ __forceinline__ unsigned pk2(float lo, float hi) { f32x2_t v = {lo, hi}; bf16x2_t b = __builtin_convertvector(v, bf16x2_t); return __builtin_bit_cast(unsigned, b); }
; __device__ __forceinline__ float bflo(unsigned w) { return __uint_as_float(w << 16); }
; __device__ __forceinline__ float bfhi(unsigned w) { return __uint_as_float(w & 0xffff0000u); }
;     __device__ __forceinline__ void operator()(const f32x4 (&acc)[2][2][4][2], const Unit& us, int wr, int wc, int fr, int fq) const {
;     ...
;                     const u32x4 g = *(const u32x4*)(gates + (unsigned)(row * NG + br * DM + col));
;                     const f32x4 v0 = acc[ai][bj][m][0], v1 = acc[ai][bj][m][1];
;                     float o[8];
;                     o[0] = bflo(g.x) * v0[0]; o[1] = bfhi(g.x) * v0[1]; o[2] = bflo(g.y) * v0[2]; o[3] = bfhi(g.y) * v0[3];
;                     o[4] = bflo(g.z) * v1[0]; o[5] = bfhi(g.z) * v1[1]; o[6] = bflo(g.w) * v1[2]; o[7] = bfhi(g.w) * v1[3];
;                     bf16_t* dst = merged + (unsigned)(row * DM + col);
;                     if (br > 0) {
;                         const u32x4 p = *(const u32x4*)dst;
;                         o[0] += bflo(p.x); o[1] += bfhi(p.x); o[2] += bflo(p.y); o[3] += bfhi(p.y);
;                         o[4] += bflo(p.z); o[5] += bfhi(p.z); o[6] += bflo(p.w); o[7] += bfhi(p.w);
;                     }
;                     u32x4 w; w.x = pk2(o[0], o[1]); w.y = pk2(o[2], o[3]); w.z = pk2(o[4], o[5]); w.w = pk2(o[6], o[7]);
;                     *(u32x4*)dst = w;
	v_lshlrev_b32_e32 v138, 16, v214
	v_and_b32_e32 v139, 0xffff0000, v214
	v_lshlrev_b32_e32 v152, 16, v215
	v_and_b32_e32 v153, 0xffff0000, v215
	v_lshlrev_b32_e32 v210, 16, v216
	v_and_b32_e32 v211, 0xffff0000, v216
	v_lshlrev_b32_e32 v202, 16, v217
	v_and_b32_e32 v203, 0xffff0000, v217
	v_pk_mul_f32 v[16:17], v[16:17], v[138:139]
	v_pk_mul_f32 v[18:19], v[18:19], v[152:153]
	v_pk_mul_f32 v[20:21], v[20:21], v[210:211]
	v_pk_mul_f32 v[22:23], v[22:23], v[202:203]
	v_lshlrev_b32_e32 v138, 16, v230
	v_and_b32_e32 v139, 0xffff0000, v230
	v_lshlrev_b32_e32 v152, 16, v231
	v_and_b32_e32 v153, 0xffff0000, v231
	v_lshlrev_b32_e32 v210, 16, v232
	v_and_b32_e32 v211, 0xffff0000, v232
	v_lshlrev_b32_e32 v202, 16, v233
	v_and_b32_e32 v203, 0xffff0000, v233
	v_pk_add_f32 v[16:17], v[16:17], v[138:139]
	v_pk_add_f32 v[18:19], v[18:19], v[152:153]
	v_pk_add_f32 v[20:21], v[20:21], v[210:211]
	v_pk_add_f32 v[22:23], v[22:23], v[202:203]
	v_cvt_pk_bf16_f32 v16, v16, v17
	v_cvt_pk_bf16_f32 v17, v18, v19
	v_cvt_pk_bf16_f32 v18, v20, v21
	v_cvt_pk_bf16_f32 v19, v22, v23
	global_store_dwordx4 v237, v[16:19], s[6:7] offset:256
	v_add_u32_e32 v237, 0x8000, v237
	s_waitcnt vmcnt(6)
	v_lshlrev_b32_e32 v138, 16, v218
	v_and_b32_e32 v139, 0xffff0000, v218
	v_lshlrev_b32_e32 v152, 16, v219
	v_and_b32_e32 v153, 0xffff0000, v219
	v_lshlrev_b32_e32 v210, 16, v220
	v_and_b32_e32 v211, 0xffff0000, v220
	v_lshlrev_b32_e32 v202, 16, v221
	v_and_b32_e32 v203, 0xffff0000, v221
	v_pk_mul_f32 v[8:9], v[8:9], v[138:139]
	v_pk_mul_f32 v[10:11], v[10:11], v[152:153]
	v_pk_mul_f32 v[12:13], v[12:13], v[210:211]
	v_pk_mul_f32 v[14:15], v[14:15], v[202:203]
	v_lshlrev_b32_e32 v138, 16, v238
	v_and_b32_e32 v139, 0xffff0000, v238
	v_lshlrev_b32_e32 v152, 16, v239
	v_and_b32_e32 v153, 0xffff0000, v239
	v_lshlrev_b32_e32 v210, 16, v240
	v_and_b32_e32 v211, 0xffff0000, v240
	v_lshlrev_b32_e32 v202, 16, v241
	v_and_b32_e32 v203, 0xffff0000, v241
	v_pk_add_f32 v[8:9], v[8:9], v[138:139]
	v_pk_add_f32 v[10:11], v[10:11], v[152:153]
	v_pk_add_f32 v[12:13], v[12:13], v[210:211]
	v_pk_add_f32 v[14:15], v[14:15], v[202:203]
	v_cvt_pk_bf16_f32 v8, v8, v9
	v_cvt_pk_bf16_f32 v9, v10, v11
	v_cvt_pk_bf16_f32 v10, v12, v13
	v_cvt_pk_bf16_f32 v11, v14, v15
	global_store_dwordx4 v237, v[8:11], s[6:7]
	s_waitcnt vmcnt(5)
	v_lshlrev_b32_e32 v138, 16, v222
	v_and_b32_e32 v139, 0xffff0000, v222
	v_lshlrev_b32_e32 v152, 16, v223
	v_and_b32_e32 v153, 0xffff0000, v223
	v_lshlrev_b32_e32 v210, 16, v224
	v_and_b32_e32 v211, 0xffff0000, v224
	v_lshlrev_b32_e32 v202, 16, v225
	v_and_b32_e32 v203, 0xffff0000, v225
	v_pk_mul_f32 v[0:1], v[0:1], v[138:139]
	v_pk_mul_f32 v[2:3], v[2:3], v[152:153]
	v_pk_mul_f32 v[4:5], v[4:5], v[210:211]
	v_pk_mul_f32 v[6:7], v[6:7], v[202:203]
	v_lshlrev_b32_e32 v138, 16, v246
	v_and_b32_e32 v139, 0xffff0000, v246
	v_lshlrev_b32_e32 v152, 16, v247
	v_and_b32_e32 v153, 0xffff0000, v247
	v_lshlrev_b32_e32 v210, 16, v248
	v_and_b32_e32 v211, 0xffff0000, v248
	v_lshlrev_b32_e32 v202, 16, v249
	v_and_b32_e32 v203, 0xffff0000, v249
	v_pk_add_f32 v[0:1], v[0:1], v[138:139]
	v_pk_add_f32 v[2:3], v[2:3], v[152:153]
	v_pk_add_f32 v[4:5], v[4:5], v[210:211]
	v_pk_add_f32 v[6:7], v[6:7], v[202:203]
	v_cvt_pk_bf16_f32 v0, v0, v1
	v_cvt_pk_bf16_f32 v1, v2, v3
	v_cvt_pk_bf16_f32 v2, v4, v5
	v_cvt_pk_bf16_f32 v3, v6, v7
	global_store_dwordx4 v237, v[0:3], s[6:7] offset:256
	s_branch .Lbr_ep_done
.Lbr_ep_first:
	global_load_dwordx4 v[154:157], v64, s[36:37]
	global_load_dwordx4 v[158:161], v64, s[36:37] offset:256
	v_add_u32_e32 v64, 0x18000, v64
	global_load_dwordx4 v[162:165], v64, s[36:37]
	global_load_dwordx4 v[166:169], v64, s[36:37] offset:256
	v_add_u32_e32 v64, 0x18000, v64
	global_load_dwordx4 v[170:173], v64, s[36:37]
	global_load_dwordx4 v[174:177], v64, s[36:37] offset:256
	v_add_u32_e32 v64, 0x18000, v64
	global_load_dwordx4 v[178:181], v64, s[36:37]
	global_load_dwordx4 v[182:185], v64, s[36:37] offset:256
	v_add_u32_e32 v64, 0x78000, v64
	global_load_dwordx4 v[186:189], v64, s[36:37]
	global_load_dwordx4 v[190:193], v64, s[36:37] offset:256
	v_add_u32_e32 v64, 0x18000, v64
	global_load_dwordx4 v[194:197], v64, s[36:37]
	global_load_dwordx4 v[198:201], v64, s[36:37] offset:256
	v_add_u32_e32 v64, 0x18000, v64
	global_load_dwordx4 v[206:209], v64, s[36:37]
	global_load_dwordx4 v[214:217], v64, s[36:37] offset:256
	v_add_u32_e32 v64, 0x18000, v64
	global_load_dwordx4 v[218:221], v64, s[36:37]
	global_load_dwordx4 v[222:225], v64, s[36:37] offset:256
	s_waitcnt vmcnt(15)
	v_lshlrev_b32_e32 v138, 16, v154
	v_and_b32_e32 v139, 0xffff0000, v154
	v_lshlrev_b32_e32 v152, 16, v155
	v_and_b32_e32 v153, 0xffff0000, v155
	v_lshlrev_b32_e32 v210, 16, v156
	v_and_b32_e32 v211, 0xffff0000, v156
	v_lshlrev_b32_e32 v202, 16, v157
	v_and_b32_e32 v203, 0xffff0000, v157
	v_pk_mul_f32 v[126:127], v[126:127], v[138:139]
	v_pk_mul_f32 v[128:129], v[128:129], v[152:153]
	v_pk_mul_f32 v[122:123], v[122:123], v[210:211]
	v_pk_mul_f32 v[124:125], v[124:125], v[202:203]
	v_cvt_pk_bf16_f32 v126, v126, v127
	v_cvt_pk_bf16_f32 v127, v128, v129
	v_cvt_pk_bf16_f32 v128, v122, v123
	v_cvt_pk_bf16_f32 v129, v124, v125
	global_store_dwordx4 v237, v[126:129], s[6:7]
	s_waitcnt vmcnt(15)
	v_lshlrev_b32_e32 v138, 16, v158
	v_and_b32_e32 v139, 0xffff0000, v158
	v_lshlrev_b32_e32 v152, 16, v159
	v_and_b32_e32 v153, 0xffff0000, v159
	v_lshlrev_b32_e32 v210, 16, v160
	v_and_b32_e32 v211, 0xffff0000, v160
	v_lshlrev_b32_e32 v202, 16, v161
	v_and_b32_e32 v203, 0xffff0000, v161
	v_pk_mul_f32 v[114:115], v[114:115], v[138:139]
	v_pk_mul_f32 v[116:117], v[116:117], v[152:153]
	v_pk_mul_f32 v[118:119], v[118:119], v[210:211]
	v_pk_mul_f32 v[120:121], v[120:121], v[202:203]
	v_cvt_pk_bf16_f32 v114, v114, v115
	v_cvt_pk_bf16_f32 v115, v116, v117
	v_cvt_pk_bf16_f32 v116, v118, v119
	v_cvt_pk_bf16_f32 v117, v120, v121
	global_store_dwordx4 v237, v[114:117], s[6:7] offset:256
	v_add_u32_e32 v237, 0x8000, v237
	s_waitcnt vmcnt(15)
; __device__ __forceinline__ unsigned pk2(float lo, float hi) { f32x2_t v = {lo, hi}; bf16x2_t b = __builtin_convertvector(v, bf16x2_t); return __builtin_bit_cast(unsigned, b); }
; __device__ __forceinline__ float bflo(unsigned w) { return __uint_as_float(w << 16); }
; __device__ __forceinline__ float bfhi(unsigned w) { return __uint_as_float(w & 0xffff0000u); }
;     __device__ __forceinline__ void operator()(const f32x4 (&acc)[2][2][4][2], const Unit& us, int wr, int wc, int fr, int fq) const {
;     ...
;                     const u32x4 g = *(const u32x4*)(gates + (unsigned)(row * NG + br * DM + col));
;                     const f32x4 v0 = acc[ai][bj][m][0], v1 = acc[ai][bj][m][1];
;                     float o[8];
;                     o[0] = bflo(g.x) * v0[0]; o[1] = bfhi(g.x) * v0[1]; o[2] = bflo(g.y) * v0[2]; o[3] = bfhi(g.y) * v0[3];
;                     o[4] = bflo(g.z) * v1[0]; o[5] = bfhi(g.z) * v1[1]; o[6] = bflo(g.w) * v1[2]; o[7] = bfhi(g.w) * v1[3];
;                     bf16_t* dst = merged + (unsigned)(row * DM + col);
;                     if (br > 0) {
;                         const u32x4 p = *(const u32x4*)dst;
;                         o[0] += bflo(p.x); o[1] += bfhi(p.x); o[2] += bflo(p.y); o[3] += bfhi(p.y);
;                         o[4] += bflo(p.z); o[5] += bfhi(p.z); o[6] += bflo(p.w); o[7] += bfhi(p.w);
;                     }
;                     u32x4 w; w.x = pk2(o[0], o[1]); w.y = pk2(o[2], o[3]); w.z = pk2(o[4], o[5]); w.w = pk2(o[6], o[7]);
;                     *(u32x4*)dst = w;
	v_lshlrev_b32_e32 v138, 16, v162
	v_and_b32_e32 v139, 0xffff0000, v162
	v_lshlrev_b32_e32 v152, 16, v163
	v_and_b32_e32 v153, 0xffff0000, v163
	v_lshlrev_b32_e32 v210, 16, v164
	v_and_b32_e32 v211, 0xffff0000, v164
	v_lshlrev_b32_e32 v202, 16, v165
	v_and_b32_e32 v203, 0xffff0000, v165
	v_pk_mul_f32 v[110:111], v[110:111], v[138:139]
	v_pk_mul_f32 v[112:113], v[112:113], v[152:153]
	v_pk_mul_f32 v[106:107], v[106:107], v[210:211]
	v_pk_mul_f32 v[108:109], v[108:109], v[202:203]
	v_cvt_pk_bf16_f32 v110, v110, v111
	v_cvt_pk_bf16_f32 v111, v112, v113
	v_cvt_pk_bf16_f32 v112, v106, v107
	v_cvt_pk_bf16_f32 v113, v108, v109
	global_store_dwordx4 v237, v[110:113], s[6:7]
	s_waitcnt vmcnt(15)
	v_lshlrev_b32_e32 v138, 16, v166
	v_and_b32_e32 v139, 0xffff0000, v166
	v_lshlrev_b32_e32 v152, 16, v167
	v_and_b32_e32 v153, 0xffff0000, v167
	v_lshlrev_b32_e32 v210, 16, v168
	v_and_b32_e32 v211, 0xffff0000, v168
	v_lshlrev_b32_e32 v202, 16, v169
	v_and_b32_e32 v203, 0xffff0000, v169
	v_pk_mul_f32 v[98:99], v[98:99], v[138:139]
	v_pk_mul_f32 v[100:101], v[100:101], v[152:153]
	v_pk_mul_f32 v[102:103], v[102:103], v[210:211]
	v_pk_mul_f32 v[104:105], v[104:105], v[202:203]
	v_cvt_pk_bf16_f32 v98, v98, v99
	v_cvt_pk_bf16_f32 v99, v100, v101
	v_cvt_pk_bf16_f32 v100, v102, v103
	v_cvt_pk_bf16_f32 v101, v104, v105
	global_store_dwordx4 v237, v[98:101], s[6:7] offset:256
	v_add_u32_e32 v237, 0x8000, v237
	s_waitcnt vmcnt(15)
	v_lshlrev_b32_e32 v138, 16, v170
	v_and_b32_e32 v139, 0xffff0000, v170
	v_lshlrev_b32_e32 v152, 16, v171
	v_and_b32_e32 v153, 0xffff0000, v171
	v_lshlrev_b32_e32 v210, 16, v172
	v_and_b32_e32 v211, 0xffff0000, v172
	v_lshlrev_b32_e32 v202, 16, v173
	v_and_b32_e32 v203, 0xffff0000, v173
	v_pk_mul_f32 v[94:95], v[94:95], v[138:139]
	v_pk_mul_f32 v[96:97], v[96:97], v[152:153]
	v_pk_mul_f32 v[90:91], v[90:91], v[210:211]
	v_pk_mul_f32 v[92:93], v[92:93], v[202:203]
	v_cvt_pk_bf16_f32 v94, v94, v95
	v_cvt_pk_bf16_f32 v95, v96, v97
	v_cvt_pk_bf16_f32 v96, v90, v91
	v_cvt_pk_bf16_f32 v97, v92, v93
	global_store_dwordx4 v237, v[94:97], s[6:7]
	s_waitcnt vmcnt(15)
	v_lshlrev_b32_e32 v138, 16, v174
	v_and_b32_e32 v139, 0xffff0000, v174
	v_lshlrev_b32_e32 v152, 16, v175
	v_and_b32_e32 v153, 0xffff0000, v175
	v_lshlrev_b32_e32 v210, 16, v176
	v_and_b32_e32 v211, 0xffff0000, v176
	v_lshlrev_b32_e32 v202, 16, v177
	v_and_b32_e32 v203, 0xffff0000, v177
	v_pk_mul_f32 v[82:83], v[82:83], v[138:139]
	v_pk_mul_f32 v[84:85], v[84:85], v[152:153]
	v_pk_mul_f32 v[86:87], v[86:87], v[210:211]
	v_pk_mul_f32 v[88:89], v[88:89], v[202:203]
	v_cvt_pk_bf16_f32 v82, v82, v83
	v_cvt_pk_bf16_f32 v83, v84, v85
	v_cvt_pk_bf16_f32 v84, v86, v87
	v_cvt_pk_bf16_f32 v85, v88, v89
	global_store_dwordx4 v237, v[82:85], s[6:7] offset:256
	v_add_u32_e32 v237, 0x8000, v237
	s_waitcnt vmcnt(15)
	v_lshlrev_b32_e32 v138, 16, v178
	v_and_b32_e32 v139, 0xffff0000, v178
	v_lshlrev_b32_e32 v152, 16, v179
	v_and_b32_e32 v153, 0xffff0000, v179
	v_lshlrev_b32_e32 v210, 16, v180
	v_and_b32_e32 v211, 0xffff0000, v180
	v_lshlrev_b32_e32 v202, 16, v181
	v_and_b32_e32 v203, 0xffff0000, v181
	v_pk_mul_f32 v[78:79], v[78:79], v[138:139]
	v_pk_mul_f32 v[80:81], v[80:81], v[152:153]
	v_pk_mul_f32 v[74:75], v[74:75], v[210:211]
	v_pk_mul_f32 v[76:77], v[76:77], v[202:203]
	v_cvt_pk_bf16_f32 v78, v78, v79
	v_cvt_pk_bf16_f32 v79, v80, v81
	v_cvt_pk_bf16_f32 v80, v74, v75
	v_cvt_pk_bf16_f32 v81, v76, v77
	global_store_dwordx4 v237, v[78:81], s[6:7]
	s_waitcnt vmcnt(15)
	v_lshlrev_b32_e32 v138, 16, v182
	v_and_b32_e32 v139, 0xffff0000, v182
	v_lshlrev_b32_e32 v152, 16, v183
	v_and_b32_e32 v153, 0xffff0000, v183
	v_lshlrev_b32_e32 v210, 16, v184
	v_and_b32_e32 v211, 0xffff0000, v184
	v_lshlrev_b32_e32 v202, 16, v185
	v_and_b32_e32 v203, 0xffff0000, v185
	v_pk_mul_f32 v[66:67], v[66:67], v[138:139]
	v_pk_mul_f32 v[68:69], v[68:69], v[152:153]
	v_pk_mul_f32 v[70:71], v[70:71], v[210:211]
	v_pk_mul_f32 v[72:73], v[72:73], v[202:203]
	v_cvt_pk_bf16_f32 v66, v66, v67
	v_cvt_pk_bf16_f32 v67, v68, v69
	v_cvt_pk_bf16_f32 v68, v70, v71
	v_cvt_pk_bf16_f32 v69, v72, v73
	global_store_dwordx4 v237, v[66:69], s[6:7] offset:256
	v_add_u32_e32 v237, 0x28000, v237
	s_waitcnt vmcnt(15)
	v_lshlrev_b32_e32 v138, 16, v186
	v_and_b32_e32 v139, 0xffff0000, v186
	v_lshlrev_b32_e32 v152, 16, v187
	v_and_b32_e32 v153, 0xffff0000, v187
	v_lshlrev_b32_e32 v210, 16, v188
	v_and_b32_e32 v211, 0xffff0000, v188
	v_lshlrev_b32_e32 v202, 16, v189
	v_and_b32_e32 v203, 0xffff0000, v189
	v_pk_mul_f32 v[60:61], v[60:61], v[138:139]
	v_pk_mul_f32 v[62:63], v[62:63], v[152:153]
	v_pk_mul_f32 v[56:57], v[56:57], v[210:211]
	v_pk_mul_f32 v[58:59], v[58:59], v[202:203]
	v_cvt_pk_bf16_f32 v60, v60, v61
	v_cvt_pk_bf16_f32 v61, v62, v63
	v_cvt_pk_bf16_f32 v62, v56, v57
	v_cvt_pk_bf16_f32 v63, v58, v59
	global_store_dwordx4 v237, v[60:63], s[6:7]
	s_waitcnt vmcnt(15)
; __device__ __forceinline__ unsigned pk2(float lo, float hi) { f32x2_t v = {lo, hi}; bf16x2_t b = __builtin_convertvector(v, bf16x2_t); return __builtin_bit_cast(unsigned, b); }
; __device__ __forceinline__ float bflo(unsigned w) { return __uint_as_float(w << 16); }
; __device__ __forceinline__ float bfhi(unsigned w) { return __uint_as_float(w & 0xffff0000u); }
;     __device__ __forceinline__ void operator()(const f32x4 (&acc)[2][2][4][2], const Unit& us, int wr, int wc, int fr, int fq) const {
;     ...
;                     const u32x4 g = *(const u32x4*)(gates + (unsigned)(row * NG + br * DM + col));
;                     const f32x4 v0 = acc[ai][bj][m][0], v1 = acc[ai][bj][m][1];
;                     float o[8];
;                     o[0] = bflo(g.x) * v0[0]; o[1] = bfhi(g.x) * v0[1]; o[2] = bflo(g.y) * v0[2]; o[3] = bfhi(g.y) * v0[3];
;                     o[4] = bflo(g.z) * v1[0]; o[5] = bfhi(g.z) * v1[1]; o[6] = bflo(g.w) * v1[2]; o[7] = bfhi(g.w) * v1[3];
;                     bf16_t* dst = merged + (unsigned)(row * DM + col);
;                     if (br > 0) {
;                         const u32x4 p = *(const u32x4*)dst;
;                         o[0] += bflo(p.x); o[1] += bfhi(p.x); o[2] += bflo(p.y); o[3] += bfhi(p.y);
;                         o[4] += bflo(p.z); o[5] += bfhi(p.z); o[6] += bflo(p.w); o[7] += bfhi(p.w);
;                     }
;                     u32x4 w; w.x = pk2(o[0], o[1]); w.y = pk2(o[2], o[3]); w.z = pk2(o[4], o[5]); w.w = pk2(o[6], o[7]);
;                     *(u32x4*)dst = w;
	v_lshlrev_b32_e32 v138, 16, v190
	v_and_b32_e32 v139, 0xffff0000, v190
	v_lshlrev_b32_e32 v152, 16, v191
	v_and_b32_e32 v153, 0xffff0000, v191
	v_lshlrev_b32_e32 v210, 16, v192
	v_and_b32_e32 v211, 0xffff0000, v192
	v_lshlrev_b32_e32 v202, 16, v193
	v_and_b32_e32 v203, 0xffff0000, v193
	v_pk_mul_f32 v[48:49], v[48:49], v[138:139]
	v_pk_mul_f32 v[50:51], v[50:51], v[152:153]
	v_pk_mul_f32 v[52:53], v[52:53], v[210:211]
	v_pk_mul_f32 v[54:55], v[54:55], v[202:203]
	v_cvt_pk_bf16_f32 v48, v48, v49
	v_cvt_pk_bf16_f32 v49, v50, v51
	v_cvt_pk_bf16_f32 v50, v52, v53
	v_cvt_pk_bf16_f32 v51, v54, v55
	global_store_dwordx4 v237, v[48:51], s[6:7] offset:256
	v_add_u32_e32 v237, 0x8000, v237
	s_waitcnt vmcnt(15)
	v_lshlrev_b32_e32 v138, 16, v194
	v_and_b32_e32 v139, 0xffff0000, v194
	v_lshlrev_b32_e32 v152, 16, v195
	v_and_b32_e32 v153, 0xffff0000, v195
	v_lshlrev_b32_e32 v210, 16, v196
	v_and_b32_e32 v211, 0xffff0000, v196
	v_lshlrev_b32_e32 v202, 16, v197
	v_and_b32_e32 v203, 0xffff0000, v197
	v_pk_mul_f32 v[44:45], v[44:45], v[138:139]
	v_pk_mul_f32 v[46:47], v[46:47], v[152:153]
	v_pk_mul_f32 v[40:41], v[40:41], v[210:211]
	v_pk_mul_f32 v[42:43], v[42:43], v[202:203]
	v_cvt_pk_bf16_f32 v44, v44, v45
	v_cvt_pk_bf16_f32 v45, v46, v47
	v_cvt_pk_bf16_f32 v46, v40, v41
	v_cvt_pk_bf16_f32 v47, v42, v43
	global_store_dwordx4 v237, v[44:47], s[6:7]
	s_waitcnt vmcnt(15)
	v_lshlrev_b32_e32 v138, 16, v198
	v_and_b32_e32 v139, 0xffff0000, v198
	v_lshlrev_b32_e32 v152, 16, v199
	v_and_b32_e32 v153, 0xffff0000, v199
	v_lshlrev_b32_e32 v210, 16, v200
	v_and_b32_e32 v211, 0xffff0000, v200
	v_lshlrev_b32_e32 v202, 16, v201
	v_and_b32_e32 v203, 0xffff0000, v201
	v_pk_mul_f32 v[32:33], v[32:33], v[138:139]
	v_pk_mul_f32 v[34:35], v[34:35], v[152:153]
	v_pk_mul_f32 v[36:37], v[36:37], v[210:211]
	v_pk_mul_f32 v[38:39], v[38:39], v[202:203]
	v_cvt_pk_bf16_f32 v32, v32, v33
	v_cvt_pk_bf16_f32 v33, v34, v35
	v_cvt_pk_bf16_f32 v34, v36, v37
	v_cvt_pk_bf16_f32 v35, v38, v39
	global_store_dwordx4 v237, v[32:35], s[6:7] offset:256
	v_add_u32_e32 v237, 0x8000, v237
	s_waitcnt vmcnt(15)
	v_lshlrev_b32_e32 v138, 16, v206
	v_and_b32_e32 v139, 0xffff0000, v206
	v_lshlrev_b32_e32 v152, 16, v207
	v_and_b32_e32 v153, 0xffff0000, v207
	v_lshlrev_b32_e32 v210, 16, v208
	v_and_b32_e32 v211, 0xffff0000, v208
	v_lshlrev_b32_e32 v202, 16, v209
	v_and_b32_e32 v203, 0xffff0000, v209
	v_pk_mul_f32 v[28:29], v[28:29], v[138:139]
	v_pk_mul_f32 v[30:31], v[30:31], v[152:153]
	v_pk_mul_f32 v[24:25], v[24:25], v[210:211]
	v_pk_mul_f32 v[26:27], v[26:27], v[202:203]
	v_cvt_pk_bf16_f32 v28, v28, v29
	v_cvt_pk_bf16_f32 v29, v30, v31
	v_cvt_pk_bf16_f32 v30, v24, v25
	v_cvt_pk_bf16_f32 v31, v26, v27
	global_store_dwordx4 v237, v[28:31], s[6:7]
	s_waitcnt vmcnt(15)
	v_lshlrev_b32_e32 v138, 16, v214
	v_and_b32_e32 v139, 0xffff0000, v214
	v_lshlrev_b32_e32 v152, 16, v215
	v_and_b32_e32 v153, 0xffff0000, v215
	v_lshlrev_b32_e32 v210, 16, v216
	v_and_b32_e32 v211, 0xffff0000, v216
	v_lshlrev_b32_e32 v202, 16, v217
	v_and_b32_e32 v203, 0xffff0000, v217
	v_pk_mul_f32 v[16:17], v[16:17], v[138:139]
	v_pk_mul_f32 v[18:19], v[18:19], v[152:153]
	v_pk_mul_f32 v[20:21], v[20:21], v[210:211]
	v_pk_mul_f32 v[22:23], v[22:23], v[202:203]
	v_cvt_pk_bf16_f32 v16, v16, v17
	v_cvt_pk_bf16_f32 v17, v18, v19
	v_cvt_pk_bf16_f32 v18, v20, v21
	v_cvt_pk_bf16_f32 v19, v22, v23
	global_store_dwordx4 v237, v[16:19], s[6:7] offset:256
	v_add_u32_e32 v237, 0x8000, v237
	s_waitcnt vmcnt(15)
	v_lshlrev_b32_e32 v138, 16, v218
	v_and_b32_e32 v139, 0xffff0000, v218
	v_lshlrev_b32_e32 v152, 16, v219
	v_and_b32_e32 v153, 0xffff0000, v219
	v_lshlrev_b32_e32 v210, 16, v220
	v_and_b32_e32 v211, 0xffff0000, v220
	v_lshlrev_b32_e32 v202, 16, v221
	v_and_b32_e32 v203, 0xffff0000, v221
	v_pk_mul_f32 v[8:9], v[8:9], v[138:139]
	v_pk_mul_f32 v[10:11], v[10:11], v[152:153]
	v_pk_mul_f32 v[12:13], v[12:13], v[210:211]
	v_pk_mul_f32 v[14:15], v[14:15], v[202:203]
	v_cvt_pk_bf16_f32 v8, v8, v9
	v_cvt_pk_bf16_f32 v9, v10, v11
	v_cvt_pk_bf16_f32 v10, v12, v13
	v_cvt_pk_bf16_f32 v11, v14, v15
	global_store_dwordx4 v237, v[8:11], s[6:7]
	s_waitcnt vmcnt(15)
	v_lshlrev_b32_e32 v138, 16, v222
	v_and_b32_e32 v139, 0xffff0000, v222
	v_lshlrev_b32_e32 v152, 16, v223
	v_and_b32_e32 v153, 0xffff0000, v223
	v_lshlrev_b32_e32 v210, 16, v224
	v_and_b32_e32 v211, 0xffff0000, v224
	v_lshlrev_b32_e32 v202, 16, v225
	v_and_b32_e32 v203, 0xffff0000, v225
	v_pk_mul_f32 v[0:1], v[0:1], v[138:139]
	v_pk_mul_f32 v[2:3], v[2:3], v[152:153]
	v_pk_mul_f32 v[4:5], v[4:5], v[210:211]
	v_pk_mul_f32 v[6:7], v[6:7], v[202:203]
	v_cvt_pk_bf16_f32 v0, v0, v1
	v_cvt_pk_bf16_f32 v1, v2, v3
	v_cvt_pk_bf16_f32 v2, v4, v5
	v_cvt_pk_bf16_f32 v3, v6, v7
	global_store_dwordx4 v237, v[0:3], s[6:7] offset:256
